# F1-i8 epilogue arithmetic regenerated: packed mul/add, interleaved 8-wide so no trans-hazard nops (same f32 ops)
# speedup vs baseline: 1.0038x; 1.0023x over previous
; __device__ __forceinline__ float sigmoidf_fast(float x) { return __builtin_amdgcn_rcpf(1.0f + __builtin_amdgcn_exp2f(-1.44269504089f * x)); }
; __device__ __forceinline__ unsigned cvt_pk4_fp8(float a, float b, float c, float d) { int w = 0; w = __builtin_amdgcn_cvt_pk_fp8_f32(a, b, w, false); w = __builtin_amdgcn_cvt_pk_fp8_f32(c, d, w, true); return (unsigned)w; }
;     __device__ __forceinline__ void operator()(const f32x4 (&acc)[2][2][4][2], const Unit& u, int wr, int wc, int fr, int fq) const {
;     ...
;             for (int m = 0; m < 4; ++m) { const size_t ro = (size_t)(row0 + ai * HALF + m * 16) * ldc + col0;
;                 float r[8]; const float scr_ = rs ? rs[row0 + ai * HALF + m * 16] * sc : sc;
; #pragma unroll
;                 for (int n = 0; n < 2; ++n)
; #pragma unroll
;                     for (int j = 0; j < 4; ++j) { const float ga = acc[ai][0][m][n][j], ua = acc[ai][1][m][n][j];
;                         const float g = (rs ? (float)__float_as_int(ga) : ga) * scr_, up = (rs ? (float)__float_as_int(ua) : ua) * scr_; r[n * 4 + j] = g * sigmoidf_fast(g) * up; }
; #pragma unroll
;                 for (int k = 0; k < 8; ++k) lm = fmaxf(lm, fabsf(r[k]));
;                 if (O8) {
; #pragma unroll
;                     for (int k = 0; k < 8; ++k) r[k] = __builtin_amdgcn_fmed3f(r[k] * s8, -448.0f, 448.0f);
;                     u32x2 w; w.x = cvt_pk4_fp8(r[0], r[1], r[2], r[3]); w.y = cvt_pk4_fp8(r[4], r[5], r[6], r[7]); *(u32x2*)(O8 + ro) = w; }
.LBB0_541:
	s_mov_b32 s98, 0xbfb8aa3b
	s_mov_b32 s99, 0xbfb8aa3b
	v_cvt_f32_i32_e32 v120, v120
	v_cvt_f32_i32_e32 v121, v121
	v_cvt_f32_i32_e32 v122, v122
	v_cvt_f32_i32_e32 v123, v123
	v_cvt_f32_i32_e32 v128, v128
	v_cvt_f32_i32_e32 v129, v129
	v_cvt_f32_i32_e32 v130, v130
	v_cvt_f32_i32_e32 v131, v131
	v_cvt_f32_i32_e32 v116, v116
	v_cvt_f32_i32_e32 v117, v117
	v_cvt_f32_i32_e32 v118, v118
	v_cvt_f32_i32_e32 v119, v119
	v_cvt_f32_i32_e32 v124, v124
	v_cvt_f32_i32_e32 v125, v125
	v_cvt_f32_i32_e32 v126, v126
	v_cvt_f32_i32_e32 v127, v127
	v_lshl_or_b32 v142, s44, 7, v155
	v_ashrrev_i32_e32 v143, 31, v142
	v_mad_i64_i32 v[148:149], s[34:35], v144, s1, v[142:143]
	s_mov_b64 s[44:45], -1
	s_and_b64 vcc, exec, s[28:29]
	s_waitcnt vmcnt(0)
	v_mul_f32_e32 v158, v154, v186
	v_pk_mul_f32 v[120:121], v[158:159], v[120:121] op_sel_hi:[0,1]
	v_pk_mul_f32 v[122:123], v[158:159], v[122:123] op_sel_hi:[0,1]
	v_pk_mul_f32 v[128:129], v[158:159], v[128:129] op_sel_hi:[0,1]
	v_pk_mul_f32 v[130:131], v[158:159], v[130:131] op_sel_hi:[0,1]
	v_pk_mul_f32 v[194:195], v[120:121], s[98:99]
	v_pk_mul_f32 v[196:197], v[122:123], s[98:99]
	v_pk_mul_f32 v[198:199], v[128:129], s[98:99]
	v_pk_mul_f32 v[200:201], v[130:131], s[98:99]
	v_pk_mul_f32 v[116:117], v[158:159], v[116:117] op_sel_hi:[0,1]
	v_pk_mul_f32 v[118:119], v[158:159], v[118:119] op_sel_hi:[0,1]
	v_pk_mul_f32 v[124:125], v[158:159], v[124:125] op_sel_hi:[0,1]
	v_pk_mul_f32 v[126:127], v[158:159], v[126:127] op_sel_hi:[0,1]
	v_exp_f32_e32 v194, v194
	v_exp_f32_e32 v195, v195
	v_exp_f32_e32 v196, v196
	v_exp_f32_e32 v197, v197
	v_exp_f32_e32 v198, v198
	v_exp_f32_e32 v199, v199
	v_exp_f32_e32 v200, v200
	v_exp_f32_e32 v201, v201
	v_pk_add_f32 v[194:195], v[194:195], 1.0 op_sel_hi:[1,0]
	v_pk_add_f32 v[196:197], v[196:197], 1.0 op_sel_hi:[1,0]
	v_pk_add_f32 v[198:199], v[198:199], 1.0 op_sel_hi:[1,0]
	v_pk_add_f32 v[200:201], v[200:201], 1.0 op_sel_hi:[1,0]
	v_rcp_f32_e32 v194, v194
	v_rcp_f32_e32 v195, v195
	v_rcp_f32_e32 v196, v196
	v_rcp_f32_e32 v197, v197
	v_rcp_f32_e32 v198, v198
	v_rcp_f32_e32 v199, v199
	v_rcp_f32_e32 v200, v200
	v_rcp_f32_e32 v201, v201
	v_pk_mul_f32 v[120:121], v[120:121], v[194:195]
	v_pk_mul_f32 v[122:123], v[122:123], v[196:197]
	v_pk_mul_f32 v[128:129], v[128:129], v[198:199]
	v_pk_mul_f32 v[130:131], v[130:131], v[200:201]
	v_pk_mul_f32 v[116:117], v[116:117], v[120:121]
	v_pk_mul_f32 v[118:119], v[118:119], v[122:123]
	v_pk_mul_f32 v[124:125], v[124:125], v[128:129]
	v_pk_mul_f32 v[126:127], v[126:127], v[130:131]
	s_cbranch_vccz .LBB0_543
	v_mul_f32_e32 v120, v151, v124
	v_med3_f32 v121, v120, s69, v228
	v_mul_f32_e32 v120, v151, v125
	v_med3_f32 v122, v120, s69, v228
	v_mul_f32_e32 v120, v151, v126
	v_med3_f32 v123, v120, s69, v228
	v_mul_f32_e32 v120, v151, v127
	v_med3_f32 v128, v120, s69, v228
	v_mul_f32_e32 v120, v151, v116
	v_med3_f32 v129, v120, s69, v228
	v_mul_f32_e32 v120, v151, v117
	v_med3_f32 v130, v120, s69, v228
	v_mul_f32_e32 v120, v151, v118
	v_med3_f32 v131, v120, s69, v228
	v_mov_b32_e32 v120, v35
	v_cvt_pk_fp8_f32 v120, v121, v122
	v_mov_b32_e32 v121, v35
	v_cvt_pk_fp8_f32 v121, v129, v130
	v_mul_f32_e32 v122, v151, v119
	v_med3_f32 v122, v122, s69, v228
	v_cvt_pk_fp8_f32 v120, v123, v128 op_sel:[0,0,1]
	v_cvt_pk_fp8_f32 v121, v131, v122 op_sel:[0,0,1]
	v_lshl_add_u64 v[122:123], s[36:37], 0, v[148:149]
	s_mov_b64 s[44:45], 0
	global_store_dwordx2 v[122:123], v[120:121], off

; __device__ __forceinline__ float sigmoidf_fast(float x) { return __builtin_amdgcn_rcpf(1.0f + __builtin_amdgcn_exp2f(-1.44269504089f * x)); }
; __device__ __forceinline__ unsigned cvt_pk4_fp8(float a, float b, float c, float d) { int w = 0; w = __builtin_amdgcn_cvt_pk_fp8_f32(a, b, w, false); w = __builtin_amdgcn_cvt_pk_fp8_f32(c, d, w, true); return (unsigned)w; }
;     __device__ __forceinline__ void operator()(const f32x4 (&acc)[2][2][4][2], const Unit& u, int wr, int wc, int fr, int fq) const {
;     ...
;             for (int m = 0; m < 4; ++m) { const size_t ro = (size_t)(row0 + ai * HALF + m * 16) * ldc + col0;
;                 float r[8]; const float scr_ = rs ? rs[row0 + ai * HALF + m * 16] * sc : sc;
; #pragma unroll
;                 for (int n = 0; n < 2; ++n)
; #pragma unroll
;                     for (int j = 0; j < 4; ++j) { const float ga = acc[ai][0][m][n][j], ua = acc[ai][1][m][n][j];
;                         const float g = (rs ? (float)__float_as_int(ga) : ga) * scr_, up = (rs ? (float)__float_as_int(ua) : ua) * scr_; r[n * 4 + j] = g * sigmoidf_fast(g) * up; }
; #pragma unroll
;                 for (int k = 0; k < 8; ++k) lm = fmaxf(lm, fabsf(r[k]));
;                 if (O8) {
; #pragma unroll
;                     for (int k = 0; k < 8; ++k) r[k] = __builtin_amdgcn_fmed3f(r[k] * s8, -448.0f, 448.0f);
;                     u32x2 w; w.x = cvt_pk4_fp8(r[0], r[1], r[2], r[3]); w.y = cvt_pk4_fp8(r[4], r[5], r[6], r[7]); *(u32x2*)(O8 + ro) = w; }
.LBB0_545:
	s_nop 1
	v_cvt_f32_i32_e32 v104, v104
	v_cvt_f32_i32_e32 v105, v105
	v_cvt_f32_i32_e32 v106, v106
	v_cvt_f32_i32_e32 v107, v107
	v_cvt_f32_i32_e32 v112, v112
	v_cvt_f32_i32_e32 v113, v113
	v_cvt_f32_i32_e32 v114, v114
	v_cvt_f32_i32_e32 v115, v115
	v_cvt_f32_i32_e32 v100, v100
	v_cvt_f32_i32_e32 v101, v101
	v_cvt_f32_i32_e32 v102, v102
	v_cvt_f32_i32_e32 v103, v103
	v_cvt_f32_i32_e32 v108, v108
	v_cvt_f32_i32_e32 v109, v109
	v_cvt_f32_i32_e32 v110, v110
	v_cvt_f32_i32_e32 v111, v111
	v_or_b32_e32 v122, 16, v144
	v_ashrrev_i32_e32 v123, 31, v122
	v_mad_i64_i32 v[120:121], s[34:35], v122, s1, v[142:143]
	s_mov_b64 s[62:63], -1
	s_andn2_b64 vcc, exec, s[28:29]
	s_movk_i32 s71, 0x6ff
	v_mul_f32_e32 v122, v154, v187
	v_pk_mul_f32 v[104:105], v[122:123], v[104:105] op_sel_hi:[0,1]
	v_pk_mul_f32 v[106:107], v[122:123], v[106:107] op_sel_hi:[0,1]
	v_pk_mul_f32 v[112:113], v[122:123], v[112:113] op_sel_hi:[0,1]
	v_pk_mul_f32 v[114:115], v[122:123], v[114:115] op_sel_hi:[0,1]
	v_pk_mul_f32 v[194:195], v[104:105], s[98:99]
	v_pk_mul_f32 v[196:197], v[106:107], s[98:99]
	v_pk_mul_f32 v[198:199], v[112:113], s[98:99]
	v_pk_mul_f32 v[200:201], v[114:115], s[98:99]
	v_pk_mul_f32 v[100:101], v[122:123], v[100:101] op_sel_hi:[0,1]
	v_pk_mul_f32 v[102:103], v[122:123], v[102:103] op_sel_hi:[0,1]
	v_pk_mul_f32 v[108:109], v[122:123], v[108:109] op_sel_hi:[0,1]
	v_pk_mul_f32 v[110:111], v[122:123], v[110:111] op_sel_hi:[0,1]
	v_exp_f32_e32 v194, v194
	v_exp_f32_e32 v195, v195
	v_exp_f32_e32 v196, v196
	v_exp_f32_e32 v197, v197
	v_exp_f32_e32 v198, v198
	v_exp_f32_e32 v199, v199
	v_exp_f32_e32 v200, v200
	v_exp_f32_e32 v201, v201
	v_pk_add_f32 v[194:195], v[194:195], 1.0 op_sel_hi:[1,0]
	v_pk_add_f32 v[196:197], v[196:197], 1.0 op_sel_hi:[1,0]
	v_pk_add_f32 v[198:199], v[198:199], 1.0 op_sel_hi:[1,0]
	v_pk_add_f32 v[200:201], v[200:201], 1.0 op_sel_hi:[1,0]
	v_rcp_f32_e32 v194, v194
	v_rcp_f32_e32 v195, v195
	v_rcp_f32_e32 v196, v196
	v_rcp_f32_e32 v197, v197
	v_rcp_f32_e32 v198, v198
	v_rcp_f32_e32 v199, v199
	v_rcp_f32_e32 v200, v200
	v_rcp_f32_e32 v201, v201
	v_pk_mul_f32 v[104:105], v[104:105], v[194:195]
	v_pk_mul_f32 v[106:107], v[106:107], v[196:197]
	v_pk_mul_f32 v[112:113], v[112:113], v[198:199]
	v_pk_mul_f32 v[114:115], v[114:115], v[200:201]
	v_pk_mul_f32 v[100:101], v[100:101], v[104:105]
	v_pk_mul_f32 v[102:103], v[102:103], v[106:107]
	v_pk_mul_f32 v[108:109], v[108:109], v[112:113]
	v_pk_mul_f32 v[110:111], v[110:111], v[114:115]
	v_cndmask_b32_e64 v104, 0, 1, s[28:29]
	v_cmp_ne_u32_e64 s[44:45], 1, v104
	s_cbranch_vccnz .LBB0_547
	v_mul_f32_e32 v104, v151, v108
	v_med3_f32 v105, v104, s69, v228
	v_mul_f32_e32 v104, v151, v109
	v_med3_f32 v106, v104, s69, v228
	v_mul_f32_e32 v104, v151, v110
	v_med3_f32 v107, v104, s69, v228
	v_mul_f32_e32 v104, v151, v111
	v_med3_f32 v112, v104, s69, v228
	v_mul_f32_e32 v104, v151, v100
	v_med3_f32 v113, v104, s69, v228
	v_mul_f32_e32 v104, v151, v101
	v_med3_f32 v114, v104, s69, v228
	v_mul_f32_e32 v104, v151, v102
	v_med3_f32 v115, v104, s69, v228
	v_mov_b32_e32 v104, v35
	v_cvt_pk_fp8_f32 v104, v105, v106
	v_mov_b32_e32 v105, v35
	v_cvt_pk_fp8_f32 v105, v113, v114
	v_mul_f32_e32 v106, v151, v103
	v_med3_f32 v106, v106, s69, v228
	v_cvt_pk_fp8_f32 v104, v107, v112 op_sel:[0,0,1]
	v_cvt_pk_fp8_f32 v105, v115, v106 op_sel:[0,0,1]
	v_lshl_add_u64 v[106:107], s[36:37], 0, v[120:121]
	s_mov_b64 s[62:63], 0
	global_store_dwordx2 v[106:107], v[104:105], off

; __device__ __forceinline__ float sigmoidf_fast(float x) { return __builtin_amdgcn_rcpf(1.0f + __builtin_amdgcn_exp2f(-1.44269504089f * x)); }
; __device__ __forceinline__ unsigned cvt_pk4_fp8(float a, float b, float c, float d) { int w = 0; w = __builtin_amdgcn_cvt_pk_fp8_f32(a, b, w, false); w = __builtin_amdgcn_cvt_pk_fp8_f32(c, d, w, true); return (unsigned)w; }
;     __device__ __forceinline__ void operator()(const f32x4 (&acc)[2][2][4][2], const Unit& u, int wr, int wc, int fr, int fq) const {
;     ...
;             for (int m = 0; m < 4; ++m) { const size_t ro = (size_t)(row0 + ai * HALF + m * 16) * ldc + col0;
;                 float r[8]; const float scr_ = rs ? rs[row0 + ai * HALF + m * 16] * sc : sc;
; #pragma unroll
;                 for (int n = 0; n < 2; ++n)
; #pragma unroll
;                     for (int j = 0; j < 4; ++j) { const float ga = acc[ai][0][m][n][j], ua = acc[ai][1][m][n][j];
;                         const float g = (rs ? (float)__float_as_int(ga) : ga) * scr_, up = (rs ? (float)__float_as_int(ua) : ua) * scr_; r[n * 4 + j] = g * sigmoidf_fast(g) * up; }
; #pragma unroll
;                 for (int k = 0; k < 8; ++k) lm = fmaxf(lm, fabsf(r[k]));
;                 if (O8) {
; #pragma unroll
;                     for (int k = 0; k < 8; ++k) r[k] = __builtin_amdgcn_fmed3f(r[k] * s8, -448.0f, 448.0f);
;                     u32x2 w; w.x = cvt_pk4_fp8(r[0], r[1], r[2], r[3]); w.y = cvt_pk4_fp8(r[4], r[5], r[6], r[7]); *(u32x2*)(O8 + ro) = w; }
.LBB0_549:
	s_nop 1
	v_cvt_f32_i32_e32 v88, v88
	v_cvt_f32_i32_e32 v89, v89
	v_cvt_f32_i32_e32 v90, v90
	v_cvt_f32_i32_e32 v91, v91
	v_cvt_f32_i32_e32 v96, v96
	v_cvt_f32_i32_e32 v97, v97
	v_cvt_f32_i32_e32 v98, v98
	v_cvt_f32_i32_e32 v99, v99
	v_cvt_f32_i32_e32 v84, v84
	v_cvt_f32_i32_e32 v85, v85
	v_cvt_f32_i32_e32 v86, v86
	v_cvt_f32_i32_e32 v87, v87
	v_cvt_f32_i32_e32 v92, v92
	v_cvt_f32_i32_e32 v93, v93
	v_cvt_f32_i32_e32 v94, v94
	v_cvt_f32_i32_e32 v95, v95
	v_or_b32_e32 v106, 32, v144
	v_ashrrev_i32_e32 v107, 31, v106
	v_mad_i64_i32 v[104:105], s[34:35], v106, s1, v[142:143]
	s_mov_b64 s[62:63], -1
	s_and_b64 vcc, exec, s[44:45]
	v_mul_f32_e32 v106, v154, v188
	v_pk_mul_f32 v[88:89], v[106:107], v[88:89] op_sel_hi:[0,1]
	v_pk_mul_f32 v[90:91], v[106:107], v[90:91] op_sel_hi:[0,1]
	v_pk_mul_f32 v[96:97], v[106:107], v[96:97] op_sel_hi:[0,1]
	v_pk_mul_f32 v[98:99], v[106:107], v[98:99] op_sel_hi:[0,1]
	v_pk_mul_f32 v[194:195], v[88:89], s[98:99]
	v_pk_mul_f32 v[196:197], v[90:91], s[98:99]
	v_pk_mul_f32 v[198:199], v[96:97], s[98:99]
	v_pk_mul_f32 v[200:201], v[98:99], s[98:99]
	v_pk_mul_f32 v[84:85], v[106:107], v[84:85] op_sel_hi:[0,1]
	v_pk_mul_f32 v[86:87], v[106:107], v[86:87] op_sel_hi:[0,1]
	v_pk_mul_f32 v[92:93], v[106:107], v[92:93] op_sel_hi:[0,1]
	v_pk_mul_f32 v[94:95], v[106:107], v[94:95] op_sel_hi:[0,1]
	v_exp_f32_e32 v194, v194
	v_exp_f32_e32 v195, v195
	v_exp_f32_e32 v196, v196
	v_exp_f32_e32 v197, v197
	v_exp_f32_e32 v198, v198
	v_exp_f32_e32 v199, v199
	v_exp_f32_e32 v200, v200
	v_exp_f32_e32 v201, v201
	v_pk_add_f32 v[194:195], v[194:195], 1.0 op_sel_hi:[1,0]
	v_pk_add_f32 v[196:197], v[196:197], 1.0 op_sel_hi:[1,0]
	v_pk_add_f32 v[198:199], v[198:199], 1.0 op_sel_hi:[1,0]
	v_pk_add_f32 v[200:201], v[200:201], 1.0 op_sel_hi:[1,0]
	v_rcp_f32_e32 v194, v194
	v_rcp_f32_e32 v195, v195
	v_rcp_f32_e32 v196, v196
	v_rcp_f32_e32 v197, v197
	v_rcp_f32_e32 v198, v198
	v_rcp_f32_e32 v199, v199
	v_rcp_f32_e32 v200, v200
	v_rcp_f32_e32 v201, v201
	v_pk_mul_f32 v[88:89], v[88:89], v[194:195]
	v_pk_mul_f32 v[90:91], v[90:91], v[196:197]
	v_pk_mul_f32 v[96:97], v[96:97], v[198:199]
	v_pk_mul_f32 v[98:99], v[98:99], v[200:201]
	v_pk_mul_f32 v[84:85], v[84:85], v[88:89]
	v_pk_mul_f32 v[86:87], v[86:87], v[90:91]
	v_pk_mul_f32 v[92:93], v[92:93], v[96:97]
	v_pk_mul_f32 v[94:95], v[94:95], v[98:99]
	s_cbranch_vccnz .LBB0_551
	v_mul_f32_e32 v88, v151, v92
	v_med3_f32 v89, v88, s69, v228
	v_mul_f32_e32 v88, v151, v93
	v_med3_f32 v90, v88, s69, v228
	v_mul_f32_e32 v88, v151, v94
	v_med3_f32 v91, v88, s69, v228
	v_mul_f32_e32 v88, v151, v95
	v_med3_f32 v96, v88, s69, v228
	v_mul_f32_e32 v88, v151, v84
	v_med3_f32 v97, v88, s69, v228
	v_mul_f32_e32 v88, v151, v85
	v_med3_f32 v98, v88, s69, v228
	v_mul_f32_e32 v88, v151, v86
	v_med3_f32 v99, v88, s69, v228
	v_mov_b32_e32 v88, v35
	v_cvt_pk_fp8_f32 v88, v89, v90
	v_mov_b32_e32 v89, v35
	v_cvt_pk_fp8_f32 v89, v97, v98
	v_mul_f32_e32 v90, v151, v87
	v_med3_f32 v90, v90, s69, v228
	v_cvt_pk_fp8_f32 v88, v91, v96 op_sel:[0,0,1]
	v_cvt_pk_fp8_f32 v89, v99, v90 op_sel:[0,0,1]
	v_lshl_add_u64 v[90:91], s[36:37], 0, v[104:105]
	s_mov_b64 s[62:63], 0
	global_store_dwordx2 v[90:91], v[88:89], off

; __device__ __forceinline__ float sigmoidf_fast(float x) { return __builtin_amdgcn_rcpf(1.0f + __builtin_amdgcn_exp2f(-1.44269504089f * x)); }
; __device__ __forceinline__ unsigned cvt_pk4_fp8(float a, float b, float c, float d) { int w = 0; w = __builtin_amdgcn_cvt_pk_fp8_f32(a, b, w, false); w = __builtin_amdgcn_cvt_pk_fp8_f32(c, d, w, true); return (unsigned)w; }
;     __device__ __forceinline__ void operator()(const f32x4 (&acc)[2][2][4][2], const Unit& u, int wr, int wc, int fr, int fq) const {
;     ...
;             for (int m = 0; m < 4; ++m) { const size_t ro = (size_t)(row0 + ai * HALF + m * 16) * ldc + col0;
;                 float r[8]; const float scr_ = rs ? rs[row0 + ai * HALF + m * 16] * sc : sc;
; #pragma unroll
;                 for (int n = 0; n < 2; ++n)
; #pragma unroll
;                     for (int j = 0; j < 4; ++j) { const float ga = acc[ai][0][m][n][j], ua = acc[ai][1][m][n][j];
;                         const float g = (rs ? (float)__float_as_int(ga) : ga) * scr_, up = (rs ? (float)__float_as_int(ua) : ua) * scr_; r[n * 4 + j] = g * sigmoidf_fast(g) * up; }
; #pragma unroll
;                 for (int k = 0; k < 8; ++k) lm = fmaxf(lm, fabsf(r[k]));
;                 if (O8) {
; #pragma unroll
;                     for (int k = 0; k < 8; ++k) r[k] = __builtin_amdgcn_fmed3f(r[k] * s8, -448.0f, 448.0f);
;                     u32x2 w; w.x = cvt_pk4_fp8(r[0], r[1], r[2], r[3]); w.y = cvt_pk4_fp8(r[4], r[5], r[6], r[7]); *(u32x2*)(O8 + ro) = w; }
.LBB0_553:
	s_nop 1
	v_cvt_f32_i32_e32 v72, v72
	v_cvt_f32_i32_e32 v73, v73
	v_cvt_f32_i32_e32 v74, v74
	v_cvt_f32_i32_e32 v75, v75
	v_cvt_f32_i32_e32 v80, v80
	v_cvt_f32_i32_e32 v81, v81
	v_cvt_f32_i32_e32 v82, v82
	v_cvt_f32_i32_e32 v83, v83
	v_cvt_f32_i32_e32 v68, v68
	v_cvt_f32_i32_e32 v69, v69
	v_cvt_f32_i32_e32 v70, v70
	v_cvt_f32_i32_e32 v71, v71
	v_cvt_f32_i32_e32 v76, v76
	v_cvt_f32_i32_e32 v77, v77
	v_cvt_f32_i32_e32 v78, v78
	v_cvt_f32_i32_e32 v79, v79
	v_or_b32_e32 v90, 48, v144
	v_ashrrev_i32_e32 v91, 31, v90
	v_mad_i64_i32 v[88:89], s[34:35], v90, s1, v[142:143]
	s_mov_b64 s[62:63], -1
	s_and_b64 vcc, exec, s[44:45]
	v_mul_f32_e32 v90, v154, v189
	v_pk_mul_f32 v[72:73], v[90:91], v[72:73] op_sel_hi:[0,1]
	v_pk_mul_f32 v[74:75], v[90:91], v[74:75] op_sel_hi:[0,1]
	v_pk_mul_f32 v[80:81], v[90:91], v[80:81] op_sel_hi:[0,1]
	v_pk_mul_f32 v[82:83], v[90:91], v[82:83] op_sel_hi:[0,1]
	v_pk_mul_f32 v[194:195], v[72:73], s[98:99]
	v_pk_mul_f32 v[196:197], v[74:75], s[98:99]
	v_pk_mul_f32 v[198:199], v[80:81], s[98:99]
	v_pk_mul_f32 v[200:201], v[82:83], s[98:99]
	v_pk_mul_f32 v[68:69], v[90:91], v[68:69] op_sel_hi:[0,1]
	v_pk_mul_f32 v[70:71], v[90:91], v[70:71] op_sel_hi:[0,1]
	v_pk_mul_f32 v[76:77], v[90:91], v[76:77] op_sel_hi:[0,1]
	v_pk_mul_f32 v[78:79], v[90:91], v[78:79] op_sel_hi:[0,1]
	v_exp_f32_e32 v194, v194
	v_exp_f32_e32 v195, v195
	v_exp_f32_e32 v196, v196
	v_exp_f32_e32 v197, v197
	v_exp_f32_e32 v198, v198
	v_exp_f32_e32 v199, v199
	v_exp_f32_e32 v200, v200
	v_exp_f32_e32 v201, v201
	v_pk_add_f32 v[194:195], v[194:195], 1.0 op_sel_hi:[1,0]
	v_pk_add_f32 v[196:197], v[196:197], 1.0 op_sel_hi:[1,0]
	v_pk_add_f32 v[198:199], v[198:199], 1.0 op_sel_hi:[1,0]
	v_pk_add_f32 v[200:201], v[200:201], 1.0 op_sel_hi:[1,0]
	v_rcp_f32_e32 v194, v194
	v_rcp_f32_e32 v195, v195
	v_rcp_f32_e32 v196, v196
	v_rcp_f32_e32 v197, v197
	v_rcp_f32_e32 v198, v198
	v_rcp_f32_e32 v199, v199
	v_rcp_f32_e32 v200, v200
	v_rcp_f32_e32 v201, v201
	v_pk_mul_f32 v[72:73], v[72:73], v[194:195]
	v_pk_mul_f32 v[74:75], v[74:75], v[196:197]
	v_pk_mul_f32 v[80:81], v[80:81], v[198:199]
	v_pk_mul_f32 v[82:83], v[82:83], v[200:201]
	v_pk_mul_f32 v[68:69], v[68:69], v[72:73]
	v_pk_mul_f32 v[70:71], v[70:71], v[74:75]
	v_pk_mul_f32 v[76:77], v[76:77], v[80:81]
	v_pk_mul_f32 v[78:79], v[78:79], v[82:83]
	s_cbranch_vccnz .LBB0_555
	v_mul_f32_e32 v72, v151, v76
	v_med3_f32 v73, v72, s69, v228
	v_mul_f32_e32 v72, v151, v77
	v_med3_f32 v74, v72, s69, v228
	v_mul_f32_e32 v72, v151, v78
	v_med3_f32 v75, v72, s69, v228
	v_mul_f32_e32 v72, v151, v79
	v_med3_f32 v80, v72, s69, v228
	v_mul_f32_e32 v72, v151, v68
	v_med3_f32 v81, v72, s69, v228
	v_mul_f32_e32 v72, v151, v69
	v_med3_f32 v82, v72, s69, v228
	v_mul_f32_e32 v72, v151, v70
	v_med3_f32 v83, v72, s69, v228
	v_mov_b32_e32 v72, v35
	v_cvt_pk_fp8_f32 v72, v73, v74
	v_mov_b32_e32 v73, v35
	v_cvt_pk_fp8_f32 v73, v81, v82
	v_mul_f32_e32 v74, v151, v71
	v_med3_f32 v74, v74, s69, v228
	v_cvt_pk_fp8_f32 v72, v75, v80 op_sel:[0,0,1]
	v_cvt_pk_fp8_f32 v73, v83, v74 op_sel:[0,0,1]
	v_lshl_add_u64 v[74:75], s[36:37], 0, v[88:89]
	s_mov_b64 s[62:63], 0
	global_store_dwordx2 v[74:75], v[72:73], off

; __device__ __forceinline__ float sigmoidf_fast(float x) { return __builtin_amdgcn_rcpf(1.0f + __builtin_amdgcn_exp2f(-1.44269504089f * x)); }
; __device__ __forceinline__ unsigned cvt_pk4_fp8(float a, float b, float c, float d) { int w = 0; w = __builtin_amdgcn_cvt_pk_fp8_f32(a, b, w, false); w = __builtin_amdgcn_cvt_pk_fp8_f32(c, d, w, true); return (unsigned)w; }
;     __device__ __forceinline__ void operator()(const f32x4 (&acc)[2][2][4][2], const Unit& u, int wr, int wc, int fr, int fq) const {
;     ...
;             for (int m = 0; m < 4; ++m) { const size_t ro = (size_t)(row0 + ai * HALF + m * 16) * ldc + col0;
;                 float r[8]; const float scr_ = rs ? rs[row0 + ai * HALF + m * 16] * sc : sc;
; #pragma unroll
;                 for (int n = 0; n < 2; ++n)
; #pragma unroll
;                     for (int j = 0; j < 4; ++j) { const float ga = acc[ai][0][m][n][j], ua = acc[ai][1][m][n][j];
;                         const float g = (rs ? (float)__float_as_int(ga) : ga) * scr_, up = (rs ? (float)__float_as_int(ua) : ua) * scr_; r[n * 4 + j] = g * sigmoidf_fast(g) * up; }
; #pragma unroll
;                 for (int k = 0; k < 8; ++k) lm = fmaxf(lm, fabsf(r[k]));
;                 if (O8) {
; #pragma unroll
;                     for (int k = 0; k < 8; ++k) r[k] = __builtin_amdgcn_fmed3f(r[k] * s8, -448.0f, 448.0f);
;                     u32x2 w; w.x = cvt_pk4_fp8(r[0], r[1], r[2], r[3]); w.y = cvt_pk4_fp8(r[4], r[5], r[6], r[7]); *(u32x2*)(O8 + ro) = w; }
.LBB0_557:
	v_cvt_f32_i32_e32 v56, v56
	v_cvt_f32_i32_e32 v57, v57
	v_cvt_f32_i32_e32 v58, v58
	v_cvt_f32_i32_e32 v59, v59
	v_cvt_f32_i32_e32 v64, v64
	v_cvt_f32_i32_e32 v65, v65
	v_cvt_f32_i32_e32 v66, v66
	v_cvt_f32_i32_e32 v67, v67
	v_cvt_f32_i32_e32 v52, v52
	v_cvt_f32_i32_e32 v53, v53
	v_cvt_f32_i32_e32 v54, v54
	v_cvt_f32_i32_e32 v55, v55
	v_cvt_f32_i32_e32 v60, v60
	v_cvt_f32_i32_e32 v61, v61
	v_cvt_f32_i32_e32 v62, v62
	v_cvt_f32_i32_e32 v63, v63
	v_add_u32_e32 v72, 0x80, v144
	v_mad_i64_i32 v[72:73], s[34:35], v72, s1, v[142:143]
	s_mov_b64 s[62:63], -1
	s_and_b64 vcc, exec, s[44:45]
	v_mul_f32_e32 v74, v154, v190
	v_pk_mul_f32 v[56:57], v[74:75], v[56:57] op_sel_hi:[0,1]
	v_pk_mul_f32 v[58:59], v[74:75], v[58:59] op_sel_hi:[0,1]
	v_pk_mul_f32 v[64:65], v[74:75], v[64:65] op_sel_hi:[0,1]
	v_pk_mul_f32 v[66:67], v[74:75], v[66:67] op_sel_hi:[0,1]
	v_pk_mul_f32 v[194:195], v[56:57], s[98:99]
	v_pk_mul_f32 v[196:197], v[58:59], s[98:99]
	v_pk_mul_f32 v[198:199], v[64:65], s[98:99]
	v_pk_mul_f32 v[200:201], v[66:67], s[98:99]
	v_pk_mul_f32 v[52:53], v[74:75], v[52:53] op_sel_hi:[0,1]
	v_pk_mul_f32 v[54:55], v[74:75], v[54:55] op_sel_hi:[0,1]
	v_pk_mul_f32 v[60:61], v[74:75], v[60:61] op_sel_hi:[0,1]
	v_pk_mul_f32 v[62:63], v[74:75], v[62:63] op_sel_hi:[0,1]
	v_exp_f32_e32 v194, v194
	v_exp_f32_e32 v195, v195
	v_exp_f32_e32 v196, v196
	v_exp_f32_e32 v197, v197
	v_exp_f32_e32 v198, v198
	v_exp_f32_e32 v199, v199
	v_exp_f32_e32 v200, v200
	v_exp_f32_e32 v201, v201
	v_pk_add_f32 v[194:195], v[194:195], 1.0 op_sel_hi:[1,0]
	v_pk_add_f32 v[196:197], v[196:197], 1.0 op_sel_hi:[1,0]
	v_pk_add_f32 v[198:199], v[198:199], 1.0 op_sel_hi:[1,0]
	v_pk_add_f32 v[200:201], v[200:201], 1.0 op_sel_hi:[1,0]
	v_rcp_f32_e32 v194, v194
	v_rcp_f32_e32 v195, v195
	v_rcp_f32_e32 v196, v196
	v_rcp_f32_e32 v197, v197
	v_rcp_f32_e32 v198, v198
	v_rcp_f32_e32 v199, v199
	v_rcp_f32_e32 v200, v200
	v_rcp_f32_e32 v201, v201
	v_pk_mul_f32 v[56:57], v[56:57], v[194:195]
	v_pk_mul_f32 v[58:59], v[58:59], v[196:197]
	v_pk_mul_f32 v[64:65], v[64:65], v[198:199]
	v_pk_mul_f32 v[66:67], v[66:67], v[200:201]
	v_pk_mul_f32 v[52:53], v[52:53], v[56:57]
	v_pk_mul_f32 v[54:55], v[54:55], v[58:59]
	v_pk_mul_f32 v[60:61], v[60:61], v[64:65]
	v_pk_mul_f32 v[62:63], v[62:63], v[66:67]
	s_cbranch_vccnz .LBB0_559
	v_mul_f32_e32 v56, v151, v60
	v_med3_f32 v57, v56, s69, v228
	v_mul_f32_e32 v56, v151, v61
	v_med3_f32 v58, v56, s69, v228
	v_mul_f32_e32 v56, v151, v62
	v_med3_f32 v59, v56, s69, v228
	v_mul_f32_e32 v56, v151, v63
	v_med3_f32 v64, v56, s69, v228
	v_mul_f32_e32 v56, v151, v52
	v_med3_f32 v65, v56, s69, v228
	v_mul_f32_e32 v56, v151, v53
	v_med3_f32 v66, v56, s69, v228
	v_mul_f32_e32 v56, v151, v54
	v_med3_f32 v67, v56, s69, v228
	v_mov_b32_e32 v56, v35
	v_cvt_pk_fp8_f32 v56, v57, v58
	v_mov_b32_e32 v57, v35
	v_cvt_pk_fp8_f32 v57, v65, v66
	v_mul_f32_e32 v58, v151, v55
	v_med3_f32 v58, v58, s69, v228
	v_cvt_pk_fp8_f32 v56, v59, v64 op_sel:[0,0,1]
	v_cvt_pk_fp8_f32 v57, v67, v58 op_sel:[0,0,1]
	v_lshl_add_u64 v[58:59], s[36:37], 0, v[72:73]
	s_mov_b64 s[62:63], 0
	global_store_dwordx2 v[58:59], v[56:57], off

; __device__ __forceinline__ float sigmoidf_fast(float x) { return __builtin_amdgcn_rcpf(1.0f + __builtin_amdgcn_exp2f(-1.44269504089f * x)); }
; __device__ __forceinline__ unsigned cvt_pk4_fp8(float a, float b, float c, float d) { int w = 0; w = __builtin_amdgcn_cvt_pk_fp8_f32(a, b, w, false); w = __builtin_amdgcn_cvt_pk_fp8_f32(c, d, w, true); return (unsigned)w; }
;     __device__ __forceinline__ void operator()(const f32x4 (&acc)[2][2][4][2], const Unit& u, int wr, int wc, int fr, int fq) const {
;     ...
;             for (int m = 0; m < 4; ++m) { const size_t ro = (size_t)(row0 + ai * HALF + m * 16) * ldc + col0;
;                 float r[8]; const float scr_ = rs ? rs[row0 + ai * HALF + m * 16] * sc : sc;
; #pragma unroll
;                 for (int n = 0; n < 2; ++n)
; #pragma unroll
;                     for (int j = 0; j < 4; ++j) { const float ga = acc[ai][0][m][n][j], ua = acc[ai][1][m][n][j];
;                         const float g = (rs ? (float)__float_as_int(ga) : ga) * scr_, up = (rs ? (float)__float_as_int(ua) : ua) * scr_; r[n * 4 + j] = g * sigmoidf_fast(g) * up; }
; #pragma unroll
;                 for (int k = 0; k < 8; ++k) lm = fmaxf(lm, fabsf(r[k]));
;                 if (O8) {
; #pragma unroll
;                     for (int k = 0; k < 8; ++k) r[k] = __builtin_amdgcn_fmed3f(r[k] * s8, -448.0f, 448.0f);
;                     u32x2 w; w.x = cvt_pk4_fp8(r[0], r[1], r[2], r[3]); w.y = cvt_pk4_fp8(r[4], r[5], r[6], r[7]); *(u32x2*)(O8 + ro) = w; }
.LBB0_561:
	v_cvt_f32_i32_e32 v40, v40
	v_cvt_f32_i32_e32 v41, v41
	v_cvt_f32_i32_e32 v42, v42
	v_cvt_f32_i32_e32 v43, v43
	v_cvt_f32_i32_e32 v48, v48
	v_cvt_f32_i32_e32 v49, v49
	v_cvt_f32_i32_e32 v50, v50
	v_cvt_f32_i32_e32 v51, v51
	v_cvt_f32_i32_e32 v36, v36
	v_cvt_f32_i32_e32 v37, v37
	v_cvt_f32_i32_e32 v38, v38
	v_cvt_f32_i32_e32 v39, v39
	v_cvt_f32_i32_e32 v44, v44
	v_cvt_f32_i32_e32 v45, v45
	v_cvt_f32_i32_e32 v46, v46
	v_cvt_f32_i32_e32 v47, v47
	v_add_u32_e32 v56, 0x90, v144
	v_mad_i64_i32 v[56:57], s[34:35], v56, s1, v[142:143]
	s_mov_b64 s[62:63], -1
	s_and_b64 vcc, exec, s[44:45]
	v_mul_f32_e32 v58, v154, v191
	v_pk_mul_f32 v[40:41], v[58:59], v[40:41] op_sel_hi:[0,1]
	v_pk_mul_f32 v[42:43], v[58:59], v[42:43] op_sel_hi:[0,1]
	v_pk_mul_f32 v[48:49], v[58:59], v[48:49] op_sel_hi:[0,1]
	v_pk_mul_f32 v[50:51], v[58:59], v[50:51] op_sel_hi:[0,1]
	v_pk_mul_f32 v[194:195], v[40:41], s[98:99]
	v_pk_mul_f32 v[196:197], v[42:43], s[98:99]
	v_pk_mul_f32 v[198:199], v[48:49], s[98:99]
	v_pk_mul_f32 v[200:201], v[50:51], s[98:99]
	v_pk_mul_f32 v[36:37], v[58:59], v[36:37] op_sel_hi:[0,1]
	v_pk_mul_f32 v[38:39], v[58:59], v[38:39] op_sel_hi:[0,1]
	v_pk_mul_f32 v[44:45], v[58:59], v[44:45] op_sel_hi:[0,1]
	v_pk_mul_f32 v[46:47], v[58:59], v[46:47] op_sel_hi:[0,1]
	v_exp_f32_e32 v194, v194
	v_exp_f32_e32 v195, v195
	v_exp_f32_e32 v196, v196
	v_exp_f32_e32 v197, v197
	v_exp_f32_e32 v198, v198
	v_exp_f32_e32 v199, v199
	v_exp_f32_e32 v200, v200
	v_exp_f32_e32 v201, v201
	v_pk_add_f32 v[194:195], v[194:195], 1.0 op_sel_hi:[1,0]
	v_pk_add_f32 v[196:197], v[196:197], 1.0 op_sel_hi:[1,0]
	v_pk_add_f32 v[198:199], v[198:199], 1.0 op_sel_hi:[1,0]
	v_pk_add_f32 v[200:201], v[200:201], 1.0 op_sel_hi:[1,0]
	v_rcp_f32_e32 v194, v194
	v_rcp_f32_e32 v195, v195
	v_rcp_f32_e32 v196, v196
	v_rcp_f32_e32 v197, v197
	v_rcp_f32_e32 v198, v198
	v_rcp_f32_e32 v199, v199
	v_rcp_f32_e32 v200, v200
	v_rcp_f32_e32 v201, v201
	v_pk_mul_f32 v[40:41], v[40:41], v[194:195]
	v_pk_mul_f32 v[42:43], v[42:43], v[196:197]
	v_pk_mul_f32 v[48:49], v[48:49], v[198:199]
	v_pk_mul_f32 v[50:51], v[50:51], v[200:201]
	v_pk_mul_f32 v[36:37], v[36:37], v[40:41]
	v_pk_mul_f32 v[38:39], v[38:39], v[42:43]
	v_pk_mul_f32 v[44:45], v[44:45], v[48:49]
	v_pk_mul_f32 v[46:47], v[46:47], v[50:51]
	s_cbranch_vccnz .LBB0_563
	v_mul_f32_e32 v40, v151, v44
	v_med3_f32 v41, v40, s69, v228
	v_mul_f32_e32 v40, v151, v45
	v_med3_f32 v42, v40, s69, v228
	v_mul_f32_e32 v40, v151, v46
	v_med3_f32 v43, v40, s69, v228
	v_mul_f32_e32 v40, v151, v47
	v_med3_f32 v48, v40, s69, v228
	v_mul_f32_e32 v40, v151, v36
	v_med3_f32 v49, v40, s69, v228
	v_mul_f32_e32 v40, v151, v37
	v_med3_f32 v50, v40, s69, v228
	v_mul_f32_e32 v40, v151, v38
	v_med3_f32 v51, v40, s69, v228
	v_mov_b32_e32 v40, v35
	v_cvt_pk_fp8_f32 v40, v41, v42
	v_mov_b32_e32 v41, v35
	v_cvt_pk_fp8_f32 v41, v49, v50
	v_mul_f32_e32 v42, v151, v39
	v_med3_f32 v42, v42, s69, v228
	v_cvt_pk_fp8_f32 v40, v43, v48 op_sel:[0,0,1]
	v_cvt_pk_fp8_f32 v41, v51, v42 op_sel:[0,0,1]
	v_lshl_add_u64 v[42:43], s[36:37], 0, v[56:57]
	s_mov_b64 s[62:63], 0
	global_store_dwordx2 v[42:43], v[40:41], off

; __device__ __forceinline__ float sigmoidf_fast(float x) { return __builtin_amdgcn_rcpf(1.0f + __builtin_amdgcn_exp2f(-1.44269504089f * x)); }
; __device__ __forceinline__ unsigned cvt_pk4_fp8(float a, float b, float c, float d) { int w = 0; w = __builtin_amdgcn_cvt_pk_fp8_f32(a, b, w, false); w = __builtin_amdgcn_cvt_pk_fp8_f32(c, d, w, true); return (unsigned)w; }
;     __device__ __forceinline__ void operator()(const f32x4 (&acc)[2][2][4][2], const Unit& u, int wr, int wc, int fr, int fq) const {
;     ...
;             for (int m = 0; m < 4; ++m) { const size_t ro = (size_t)(row0 + ai * HALF + m * 16) * ldc + col0;
;                 float r[8]; const float scr_ = rs ? rs[row0 + ai * HALF + m * 16] * sc : sc;
; #pragma unroll
;                 for (int n = 0; n < 2; ++n)
; #pragma unroll
;                     for (int j = 0; j < 4; ++j) { const float ga = acc[ai][0][m][n][j], ua = acc[ai][1][m][n][j];
;                         const float g = (rs ? (float)__float_as_int(ga) : ga) * scr_, up = (rs ? (float)__float_as_int(ua) : ua) * scr_; r[n * 4 + j] = g * sigmoidf_fast(g) * up; }
; #pragma unroll
;                 for (int k = 0; k < 8; ++k) lm = fmaxf(lm, fabsf(r[k]));
;                 if (O8) {
; #pragma unroll
;                     for (int k = 0; k < 8; ++k) r[k] = __builtin_amdgcn_fmed3f(r[k] * s8, -448.0f, 448.0f);
;                     u32x2 w; w.x = cvt_pk4_fp8(r[0], r[1], r[2], r[3]); w.y = cvt_pk4_fp8(r[4], r[5], r[6], r[7]); *(u32x2*)(O8 + ro) = w; }
.LBB0_565:
	v_cvt_f32_i32_e32 v22, v22
	v_cvt_f32_i32_e32 v23, v23
	v_cvt_f32_i32_e32 v24, v24
	v_cvt_f32_i32_e32 v25, v25
	v_cvt_f32_i32_e32 v30, v30
	v_cvt_f32_i32_e32 v31, v31
	v_cvt_f32_i32_e32 v32, v32
	v_cvt_f32_i32_e32 v33, v33
	v_cvt_f32_i32_e32 v18, v18
	v_cvt_f32_i32_e32 v19, v19
	v_cvt_f32_i32_e32 v20, v20
	v_cvt_f32_i32_e32 v21, v21
	v_cvt_f32_i32_e32 v26, v26
	v_cvt_f32_i32_e32 v27, v27
	v_cvt_f32_i32_e32 v28, v28
	v_cvt_f32_i32_e32 v29, v29
	v_add_u32_e32 v40, 0xa0, v144
	v_mad_i64_i32 v[40:41], s[34:35], v40, s1, v[142:143]
	s_mov_b64 s[62:63], -1
	s_and_b64 vcc, exec, s[44:45]
	v_mul_f32_e32 v42, v154, v192
	v_pk_mul_f32 v[22:23], v[42:43], v[22:23] op_sel_hi:[0,1]
	v_pk_mul_f32 v[24:25], v[42:43], v[24:25] op_sel_hi:[0,1]
	v_pk_mul_f32 v[30:31], v[42:43], v[30:31] op_sel_hi:[0,1]
	v_pk_mul_f32 v[32:33], v[42:43], v[32:33] op_sel_hi:[0,1]
	v_pk_mul_f32 v[194:195], v[22:23], s[98:99]
	v_pk_mul_f32 v[196:197], v[24:25], s[98:99]
	v_pk_mul_f32 v[198:199], v[30:31], s[98:99]
	v_pk_mul_f32 v[200:201], v[32:33], s[98:99]
	v_pk_mul_f32 v[18:19], v[42:43], v[18:19] op_sel_hi:[0,1]
	v_pk_mul_f32 v[20:21], v[42:43], v[20:21] op_sel_hi:[0,1]
	v_pk_mul_f32 v[26:27], v[42:43], v[26:27] op_sel_hi:[0,1]
	v_pk_mul_f32 v[28:29], v[42:43], v[28:29] op_sel_hi:[0,1]
	v_exp_f32_e32 v194, v194
	v_exp_f32_e32 v195, v195
	v_exp_f32_e32 v196, v196
	v_exp_f32_e32 v197, v197
	v_exp_f32_e32 v198, v198
	v_exp_f32_e32 v199, v199
	v_exp_f32_e32 v200, v200
	v_exp_f32_e32 v201, v201
	v_pk_add_f32 v[194:195], v[194:195], 1.0 op_sel_hi:[1,0]
	v_pk_add_f32 v[196:197], v[196:197], 1.0 op_sel_hi:[1,0]
	v_pk_add_f32 v[198:199], v[198:199], 1.0 op_sel_hi:[1,0]
	v_pk_add_f32 v[200:201], v[200:201], 1.0 op_sel_hi:[1,0]
	v_rcp_f32_e32 v194, v194
	v_rcp_f32_e32 v195, v195
	v_rcp_f32_e32 v196, v196
	v_rcp_f32_e32 v197, v197
	v_rcp_f32_e32 v198, v198
	v_rcp_f32_e32 v199, v199
	v_rcp_f32_e32 v200, v200
	v_rcp_f32_e32 v201, v201
	v_pk_mul_f32 v[22:23], v[22:23], v[194:195]
	v_pk_mul_f32 v[24:25], v[24:25], v[196:197]
	v_pk_mul_f32 v[30:31], v[30:31], v[198:199]
	v_pk_mul_f32 v[32:33], v[32:33], v[200:201]
	v_pk_mul_f32 v[18:19], v[18:19], v[22:23]
	v_pk_mul_f32 v[20:21], v[20:21], v[24:25]
	v_pk_mul_f32 v[26:27], v[26:27], v[30:31]
	v_pk_mul_f32 v[28:29], v[28:29], v[32:33]
	s_cbranch_vccnz .LBB0_567
	v_mul_f32_e32 v22, v151, v26
	v_med3_f32 v23, v22, s69, v228
	v_mul_f32_e32 v22, v151, v27
	v_med3_f32 v24, v22, s69, v228
	v_mul_f32_e32 v22, v151, v28
	v_med3_f32 v25, v22, s69, v228
	v_mul_f32_e32 v22, v151, v29
	v_med3_f32 v30, v22, s69, v228
	v_mul_f32_e32 v22, v151, v18
	v_med3_f32 v31, v22, s69, v228
	v_mul_f32_e32 v22, v151, v19
	v_med3_f32 v32, v22, s69, v228
	v_mul_f32_e32 v22, v151, v20
	v_med3_f32 v33, v22, s69, v228
	v_mov_b32_e32 v22, v35
	v_cvt_pk_fp8_f32 v22, v23, v24
	v_mov_b32_e32 v23, v35
	v_cvt_pk_fp8_f32 v23, v31, v32
	v_mul_f32_e32 v24, v151, v21
	v_med3_f32 v24, v24, s69, v228
	v_cvt_pk_fp8_f32 v22, v25, v30 op_sel:[0,0,1]
	v_cvt_pk_fp8_f32 v23, v33, v24 op_sel:[0,0,1]
	v_lshl_add_u64 v[24:25], s[36:37], 0, v[40:41]
	s_mov_b64 s[62:63], 0
	global_store_dwordx2 v[24:25], v[22:23], off

; __device__ __forceinline__ float sigmoidf_fast(float x) { return __builtin_amdgcn_rcpf(1.0f + __builtin_amdgcn_exp2f(-1.44269504089f * x)); }
; __device__ __forceinline__ unsigned cvt_pk4_fp8(float a, float b, float c, float d) { int w = 0; w = __builtin_amdgcn_cvt_pk_fp8_f32(a, b, w, false); w = __builtin_amdgcn_cvt_pk_fp8_f32(c, d, w, true); return (unsigned)w; }
;     __device__ __forceinline__ void operator()(const f32x4 (&acc)[2][2][4][2], const Unit& u, int wr, int wc, int fr, int fq) const {
;     ...
;             for (int m = 0; m < 4; ++m) { const size_t ro = (size_t)(row0 + ai * HALF + m * 16) * ldc + col0;
;                 float r[8]; const float scr_ = rs ? rs[row0 + ai * HALF + m * 16] * sc : sc;
; #pragma unroll
;                 for (int n = 0; n < 2; ++n)
; #pragma unroll
;                     for (int j = 0; j < 4; ++j) { const float ga = acc[ai][0][m][n][j], ua = acc[ai][1][m][n][j];
;                         const float g = (rs ? (float)__float_as_int(ga) : ga) * scr_, up = (rs ? (float)__float_as_int(ua) : ua) * scr_; r[n * 4 + j] = g * sigmoidf_fast(g) * up; }
; #pragma unroll
;                 for (int k = 0; k < 8; ++k) lm = fmaxf(lm, fabsf(r[k]));
;                 if (O8) {
; #pragma unroll
;                     for (int k = 0; k < 8; ++k) r[k] = __builtin_amdgcn_fmed3f(r[k] * s8, -448.0f, 448.0f);
;                     u32x2 w; w.x = cvt_pk4_fp8(r[0], r[1], r[2], r[3]); w.y = cvt_pk4_fp8(r[4], r[5], r[6], r[7]); *(u32x2*)(O8 + ro) = w; }
.LBB0_569:
	v_cvt_f32_i32_e32 v6, v6
	v_cvt_f32_i32_e32 v7, v7
	v_cvt_f32_i32_e32 v8, v8
	v_cvt_f32_i32_e32 v9, v9
	v_cvt_f32_i32_e32 v14, v14
	v_cvt_f32_i32_e32 v15, v15
	v_cvt_f32_i32_e32 v16, v16
	v_cvt_f32_i32_e32 v17, v17
	v_cvt_f32_i32_e32 v2, v2
	v_cvt_f32_i32_e32 v3, v3
	v_cvt_f32_i32_e32 v4, v4
	v_cvt_f32_i32_e32 v5, v5
	v_cvt_f32_i32_e32 v10, v10
	v_cvt_f32_i32_e32 v11, v11
	v_cvt_f32_i32_e32 v12, v12
	v_cvt_f32_i32_e32 v13, v13
	v_add_u32_e32 v22, 0xb0, v144
	v_mad_i64_i32 v[22:23], s[34:35], v22, s1, v[142:143]
	s_mov_b64 s[62:63], -1
	s_and_b64 vcc, exec, s[44:45]
	v_mul_f32_e32 v24, v154, v193
	v_pk_mul_f32 v[6:7], v[24:25], v[6:7] op_sel_hi:[0,1]
	v_pk_mul_f32 v[8:9], v[24:25], v[8:9] op_sel_hi:[0,1]
	v_pk_mul_f32 v[14:15], v[24:25], v[14:15] op_sel_hi:[0,1]
	v_pk_mul_f32 v[16:17], v[24:25], v[16:17] op_sel_hi:[0,1]
	v_pk_mul_f32 v[194:195], v[6:7], s[98:99]
	v_pk_mul_f32 v[196:197], v[8:9], s[98:99]
	v_pk_mul_f32 v[198:199], v[14:15], s[98:99]
	v_pk_mul_f32 v[200:201], v[16:17], s[98:99]
	v_pk_mul_f32 v[2:3], v[24:25], v[2:3] op_sel_hi:[0,1]
	v_pk_mul_f32 v[4:5], v[24:25], v[4:5] op_sel_hi:[0,1]
	v_pk_mul_f32 v[10:11], v[24:25], v[10:11] op_sel_hi:[0,1]
	v_pk_mul_f32 v[12:13], v[24:25], v[12:13] op_sel_hi:[0,1]
	v_exp_f32_e32 v194, v194
	v_exp_f32_e32 v195, v195
	v_exp_f32_e32 v196, v196
	v_exp_f32_e32 v197, v197
	v_exp_f32_e32 v198, v198
	v_exp_f32_e32 v199, v199
	v_exp_f32_e32 v200, v200
	v_exp_f32_e32 v201, v201
	v_pk_add_f32 v[194:195], v[194:195], 1.0 op_sel_hi:[1,0]
	v_pk_add_f32 v[196:197], v[196:197], 1.0 op_sel_hi:[1,0]
	v_pk_add_f32 v[198:199], v[198:199], 1.0 op_sel_hi:[1,0]
	v_pk_add_f32 v[200:201], v[200:201], 1.0 op_sel_hi:[1,0]
	v_rcp_f32_e32 v194, v194
	v_rcp_f32_e32 v195, v195
	v_rcp_f32_e32 v196, v196
	v_rcp_f32_e32 v197, v197
	v_rcp_f32_e32 v198, v198
	v_rcp_f32_e32 v199, v199
	v_rcp_f32_e32 v200, v200
	v_rcp_f32_e32 v201, v201
	v_pk_mul_f32 v[6:7], v[6:7], v[194:195]
	v_pk_mul_f32 v[8:9], v[8:9], v[196:197]
	v_pk_mul_f32 v[14:15], v[14:15], v[198:199]
	v_pk_mul_f32 v[16:17], v[16:17], v[200:201]
	v_pk_mul_f32 v[2:3], v[2:3], v[6:7]
	v_pk_mul_f32 v[4:5], v[4:5], v[8:9]
	v_pk_mul_f32 v[10:11], v[10:11], v[14:15]
	v_pk_mul_f32 v[12:13], v[12:13], v[16:17]
	s_cbranch_vccnz .LBB0_573
	v_mul_f32_e32 v6, v151, v10
	v_med3_f32 v7, v6, s69, v228
	v_mul_f32_e32 v6, v151, v11
	v_med3_f32 v8, v6, s69, v228
	v_mul_f32_e32 v6, v151, v12
	v_med3_f32 v9, v6, s69, v228
	v_mul_f32_e32 v6, v151, v13
	v_med3_f32 v14, v6, s69, v228
	v_mul_f32_e32 v6, v151, v2
	v_med3_f32 v15, v6, s69, v228
	v_mul_f32_e32 v6, v151, v3
	v_med3_f32 v16, v6, s69, v228
	v_mul_f32_e32 v6, v151, v4
	v_med3_f32 v17, v6, s69, v228
	v_mov_b32_e32 v6, v35
	v_cvt_pk_fp8_f32 v6, v7, v8
	v_mov_b32_e32 v7, v35
	v_cvt_pk_fp8_f32 v7, v15, v16
	v_mul_f32_e32 v8, v151, v5
	v_med3_f32 v8, v8, s69, v228
	v_cvt_pk_fp8_f32 v6, v9, v14 op_sel:[0,0,1]
	v_cvt_pk_fp8_f32 v7, v17, v8 op_sel:[0,0,1]
	v_lshl_add_u64 v[8:9], s[36:37], 0, v[22:23]
	global_store_dwordx2 v[8:9], v[6:7], off
	s_cbranch_execz .LBB0_574
